# layer-1 early weights (F1I, IN, F1O; 5120 items) converted inside layer 0's token-mixer phase (one call per CU between mixer units, staggered by CU) instead of up front; on top of k-snake + scalar-bas
# speedup vs baseline: 1.0013x; 1.0013x over previous
.LBB0_10:
	s_movk_i32 s0, 0x1400
	v_writelane_b32 v247, s0, 0
	s_movk_i32 s0, 0x1000
	s_nop 0
	v_writelane_b32 v247, s0, 8
	s_movk_i32 s0, 0x7fff
	s_nop 0
	v_writelane_b32 v247, s0, 9
	s_mov_b32 s0, 0
	s_nop 1
	v_writelane_b32 v247, s0, 1
	s_nop 1
	v_writelane_b32 v247, s0, 3
	s_nop 1
	v_writelane_b32 v247, s0, 6
	s_movk_i32 s0, 0xb00
	s_nop 0
	v_writelane_b32 v247, s0, 2
	s_movk_i32 s0, 0x1400
	s_nop 0
	v_writelane_b32 v247, s0, 5
	s_waitcnt lgkmcnt(0)
	s_lshl_b32 s0, s66, 3
	s_nop 0
	v_writelane_b32 v247, s0, 4
	s_lshr_b32 s100, s2, 6
	s_lshl_b32 s0, s74, 3
	s_add_i32 s100, s100, s0

.LBB0_129:
	v_readlane_b32 s4, v247, 6
	s_nop 0
	s_cmp_eq_u32 s4, 2
	s_cbranch_scc1 .Lwin2_ret_stub
	s_cmp_lg_u32 s4, 0
	s_cbranch_scc1 .Lwin_ret_stub
	v_readlane_b32 s4, v241, 2
	v_readlane_b32 s5, v241, 3

.LBB0_403:
	s_cmp_lg_u32 s70, 1
	s_cbranch_scc1 .Lwin2_skip
	s_lshr_b32 s100, s2, 8
	s_and_b32 s101, s74, 3
	s_add_u32 s101, s101, 1
	s_cmp_lg_u32 s100, s101
	s_cbranch_scc1 .Lwin2_skip
	v_writelane_b32 v242, s0, 0
	s_nop 1
	v_writelane_b32 v242, s1, 1
	s_nop 1
	v_writelane_b32 v242, s2, 2
	s_nop 1
	v_writelane_b32 v242, s3, 3
	s_nop 1
	v_writelane_b32 v242, s4, 4
	s_nop 1
	v_writelane_b32 v242, s5, 5
	s_nop 1
	v_writelane_b32 v242, s6, 6
	s_nop 1
	v_writelane_b32 v242, s7, 7
	s_nop 1
	v_writelane_b32 v242, s8, 8
	s_nop 1
	v_writelane_b32 v242, s9, 9
	s_nop 1
	v_writelane_b32 v242, s10, 10
	s_nop 1
	v_writelane_b32 v242, s11, 11
	s_nop 1
	v_writelane_b32 v242, s12, 12
	s_nop 1
	v_writelane_b32 v242, s13, 13
	s_nop 1
	v_writelane_b32 v242, s14, 14
	s_nop 1
	v_writelane_b32 v242, s15, 15
	s_nop 1
	v_writelane_b32 v242, s16, 16
	s_nop 1
	v_writelane_b32 v242, s17, 17
	s_nop 1
	v_writelane_b32 v242, s18, 18
	s_nop 1
	v_writelane_b32 v242, s19, 19
	s_nop 1
	v_writelane_b32 v242, s20, 20
	s_nop 1
	v_writelane_b32 v242, s21, 21
	s_nop 1
	v_writelane_b32 v242, s22, 22
	s_nop 1
	v_writelane_b32 v242, s23, 23
	s_nop 1
	v_writelane_b32 v242, s24, 24
	s_nop 1
	v_writelane_b32 v242, s25, 25
	s_nop 1
	v_writelane_b32 v242, s26, 26
	s_nop 1
	v_writelane_b32 v242, s27, 27
	s_nop 1
	v_writelane_b32 v242, s28, 28
	s_nop 1
	v_writelane_b32 v242, s29, 29
	s_nop 1
	v_writelane_b32 v242, s30, 30
	s_nop 1
	v_writelane_b32 v242, s31, 31
	s_nop 1
	v_writelane_b32 v242, s32, 32
	s_nop 1
	v_writelane_b32 v242, s33, 33
	s_nop 1
	v_writelane_b32 v242, s34, 34
	s_nop 1
	v_writelane_b32 v242, s35, 35
	s_nop 1
	v_writelane_b32 v242, s36, 36
	s_nop 1
	v_writelane_b32 v242, s37, 37
	s_nop 1
	v_writelane_b32 v242, s38, 38
	s_nop 1
	v_writelane_b32 v242, s39, 39
	s_nop 1
	v_writelane_b32 v242, s40, 40
	s_nop 1
	v_writelane_b32 v242, s41, 41
	s_nop 1
	v_writelane_b32 v242, s42, 42
	s_nop 1
	v_writelane_b32 v242, s43, 43
	s_nop 1
	v_writelane_b32 v242, s44, 44
	s_nop 1
	v_writelane_b32 v242, s45, 45
	s_nop 1
	v_writelane_b32 v242, s46, 46
	s_nop 1
	v_writelane_b32 v242, s47, 47
	s_nop 1
	v_writelane_b32 v242, s48, 48
	s_nop 1
	v_writelane_b32 v242, s49, 49
	s_nop 1
	v_writelane_b32 v242, s50, 50
	s_nop 1
	v_writelane_b32 v242, s51, 51
	s_nop 1
	v_writelane_b32 v242, s52, 52
	s_nop 1
	v_writelane_b32 v242, s53, 53
	s_nop 1
	v_writelane_b32 v242, s54, 54
	s_nop 1
	v_writelane_b32 v242, s55, 55
	s_nop 1
	v_writelane_b32 v242, s56, 56
	s_nop 1
	v_writelane_b32 v242, s57, 57
	s_nop 1
	v_writelane_b32 v242, s58, 58
	s_nop 1
	v_writelane_b32 v242, s59, 59
	s_nop 1
	v_writelane_b32 v242, s60, 60
	s_nop 1
	v_writelane_b32 v242, s61, 61
	s_nop 1
	v_writelane_b32 v242, s62, 62
	s_nop 1
	v_writelane_b32 v242, s63, 63
	s_nop 1
	v_writelane_b32 v243, s64, 0
	s_nop 1
	v_writelane_b32 v243, s65, 1
	s_nop 1
	v_writelane_b32 v243, s66, 2
	s_nop 1
	v_writelane_b32 v243, s67, 3
	s_nop 1
	v_writelane_b32 v243, s68, 4
	s_nop 1
	v_writelane_b32 v243, s69, 5
	s_nop 1
	v_writelane_b32 v243, s70, 6
	s_nop 1
	v_writelane_b32 v243, s71, 7
	s_nop 1
	v_writelane_b32 v243, s72, 8
	s_nop 1
	v_writelane_b32 v243, s73, 9
	s_nop 1
	v_writelane_b32 v243, s74, 10
	s_nop 1
	v_writelane_b32 v243, s75, 11
	s_nop 1
	v_writelane_b32 v243, s76, 12
	s_nop 1
	v_writelane_b32 v243, s77, 13
	s_nop 1
	v_writelane_b32 v243, s78, 14
	s_nop 1
	v_writelane_b32 v243, s79, 15
	s_nop 1
	v_writelane_b32 v243, s80, 16
	s_nop 1
	v_writelane_b32 v243, s81, 17
	s_nop 1
	v_writelane_b32 v243, s82, 18
	s_nop 1
	v_writelane_b32 v243, s83, 19
	s_nop 1
	v_writelane_b32 v243, s84, 20
	s_nop 1
	v_writelane_b32 v243, s85, 21
	s_nop 1
	v_writelane_b32 v243, s86, 22
	s_nop 1
	v_writelane_b32 v243, s87, 23
	s_nop 1
	v_writelane_b32 v243, s88, 24
	s_nop 1
	v_writelane_b32 v243, s89, 25
	s_nop 1
	v_writelane_b32 v243, s90, 26
	s_nop 1
	v_writelane_b32 v243, s91, 27
	s_nop 1
	v_writelane_b32 v243, s92, 28
	s_nop 1
	v_writelane_b32 v243, s93, 29
	s_nop 1
	v_writelane_b32 v243, s94, 30
	s_nop 1
	v_writelane_b32 v243, s95, 31
	s_nop 1
	v_writelane_b32 v243, s96, 32
	s_nop 1
	v_writelane_b32 v243, s97, 33
	s_nop 1
	v_writelane_b32 v243, s98, 34
	s_nop 1
	v_writelane_b32 v243, s99, 35
	s_nop 1
	v_writelane_b32 v243, vcc_lo, 36
	s_nop 1
	v_writelane_b32 v243, vcc_hi, 37
	s_mov_b64 s[0:1], exec
	s_nop 1
	v_writelane_b32 v243, s0, 38
	s_nop 1
	v_writelane_b32 v243, s1, 39
	s_mov_b64 exec, -1
	v_mov_b32_e32 v244, v241
	v_mov_b32_e32 v245, v4
	v_mov_b32_e32 v246, v33
	s_movk_i32 s4, 0x7fff
	s_nop 0
	v_writelane_b32 v247, s4, 0
	s_nop 1
	s_movk_i32 s4, 0
	s_nop 0
	v_writelane_b32 v247, s4, 1
	s_nop 1
	s_movk_i32 s4, 0xb00
	s_nop 0
	v_writelane_b32 v247, s4, 2
	s_nop 1
	s_movk_i32 s4, 1
	s_nop 0
	v_writelane_b32 v247, s4, 3
	s_nop 1
	s_movk_i32 s4, 0x800
	s_nop 0
	v_writelane_b32 v247, s4, 4
	s_nop 1
	s_movk_i32 s4, 0x1400
	s_nop 0
	v_writelane_b32 v247, s4, 5
	s_nop 1
	s_movk_i32 s4, 2
	s_nop 0
	v_writelane_b32 v247, s4, 6
	s_nop 1
	s_movk_i32 s4, 0x7fff
	s_nop 0
	v_writelane_b32 v247, s4, 8
	s_nop 1
	s_movk_i32 s4, 0x7fff
	s_nop 0
	v_writelane_b32 v247, s4, 9
	s_nop 1
	s_load_dwordx8 s[8:15], s[30:31], 0x0
	s_load_dwordx4 s[24:27], s[30:31], 0x20
	s_load_dwordx2 s[6:7], s[30:31], 0x30
	s_load_dwordx4 s[64:67], s[30:31], 0xb0
	v_readfirstlane_b32 s2, v156
	s_lshl_b32 s4, s74, 3
	s_lshr_b32 s100, s2, 6
	s_add_i32 s100, s100, s4
	s_waitcnt lgkmcnt(0)
	s_branch .Lconv_pre
.Lwin2_ret_stub:
	s_mov_b64 exec, -1
	s_waitcnt vmcnt(0) lgkmcnt(0)
	v_mov_b32_e32 v241, v244
	v_mov_b32_e32 v4, v245
	v_mov_b32_e32 v33, v246
	v_mov_b32_e32 v2, 0
	v_lshlrev_b32_e32 v158, 2, v157
	v_mov_b32_e32 v159, 0x3727c5ac
	v_mov_b64_e32 v[160:161], 0xb00
	v_mov_b64_e32 v[162:163], 0xaff
	v_mov_b64_e32 v[164:165], 0x380
	v_mov_b64_e32 v[166:167], 0x37f
	v_mov_b64_e32 v[168:169], 0x200
	v_mov_b64_e32 v[170:171], 0x1ff
	v_readlane_b32 s0, v243, 38
	v_readlane_b32 s1, v243, 39
	s_nop 1
	s_mov_b64 exec, s[0:1]
	v_readlane_b32 vcc_lo, v243, 36
	v_readlane_b32 vcc_hi, v243, 37
	v_readlane_b32 s0, v242, 0
	v_readlane_b32 s1, v242, 1
	v_readlane_b32 s2, v242, 2
	v_readlane_b32 s3, v242, 3
	v_readlane_b32 s4, v242, 4
	v_readlane_b32 s5, v242, 5
	v_readlane_b32 s6, v242, 6
	v_readlane_b32 s7, v242, 7
	v_readlane_b32 s8, v242, 8
	v_readlane_b32 s9, v242, 9
	v_readlane_b32 s10, v242, 10
	v_readlane_b32 s11, v242, 11
	v_readlane_b32 s12, v242, 12
	v_readlane_b32 s13, v242, 13
	v_readlane_b32 s14, v242, 14
	v_readlane_b32 s15, v242, 15
	v_readlane_b32 s16, v242, 16
	v_readlane_b32 s17, v242, 17
	v_readlane_b32 s18, v242, 18
	v_readlane_b32 s19, v242, 19
	v_readlane_b32 s20, v242, 20
	v_readlane_b32 s21, v242, 21
	v_readlane_b32 s22, v242, 22
	v_readlane_b32 s23, v242, 23
	v_readlane_b32 s24, v242, 24
	v_readlane_b32 s25, v242, 25
	v_readlane_b32 s26, v242, 26
	v_readlane_b32 s27, v242, 27
	v_readlane_b32 s28, v242, 28
	v_readlane_b32 s29, v242, 29
	v_readlane_b32 s30, v242, 30
	v_readlane_b32 s31, v242, 31
	v_readlane_b32 s32, v242, 32
	v_readlane_b32 s33, v242, 33
	v_readlane_b32 s34, v242, 34
	v_readlane_b32 s35, v242, 35
	v_readlane_b32 s36, v242, 36
	v_readlane_b32 s37, v242, 37
	v_readlane_b32 s38, v242, 38
	v_readlane_b32 s39, v242, 39
	v_readlane_b32 s40, v242, 40
	v_readlane_b32 s41, v242, 41
	v_readlane_b32 s42, v242, 42
	v_readlane_b32 s43, v242, 43
	v_readlane_b32 s44, v242, 44
	v_readlane_b32 s45, v242, 45
	v_readlane_b32 s46, v242, 46
	v_readlane_b32 s47, v242, 47
	v_readlane_b32 s48, v242, 48
	v_readlane_b32 s49, v242, 49
	v_readlane_b32 s50, v242, 50
	v_readlane_b32 s51, v242, 51
	v_readlane_b32 s52, v242, 52
	v_readlane_b32 s53, v242, 53
	v_readlane_b32 s54, v242, 54
	v_readlane_b32 s55, v242, 55
	v_readlane_b32 s56, v242, 56
	v_readlane_b32 s57, v242, 57
	v_readlane_b32 s58, v242, 58
	v_readlane_b32 s59, v242, 59
	v_readlane_b32 s60, v242, 60
	v_readlane_b32 s61, v242, 61
	v_readlane_b32 s62, v242, 62
	v_readlane_b32 s63, v242, 63
	v_readlane_b32 s64, v243, 0
	v_readlane_b32 s65, v243, 1
	v_readlane_b32 s66, v243, 2
	v_readlane_b32 s67, v243, 3
	v_readlane_b32 s68, v243, 4
	v_readlane_b32 s69, v243, 5
	v_readlane_b32 s70, v243, 6
	v_readlane_b32 s71, v243, 7
	v_readlane_b32 s72, v243, 8
	v_readlane_b32 s73, v243, 9
	v_readlane_b32 s74, v243, 10
	v_readlane_b32 s75, v243, 11
	v_readlane_b32 s76, v243, 12
	v_readlane_b32 s77, v243, 13
	v_readlane_b32 s78, v243, 14
	v_readlane_b32 s79, v243, 15
	v_readlane_b32 s80, v243, 16
	v_readlane_b32 s81, v243, 17
	v_readlane_b32 s82, v243, 18
	v_readlane_b32 s83, v243, 19
	v_readlane_b32 s84, v243, 20
	v_readlane_b32 s85, v243, 21
	v_readlane_b32 s86, v243, 22
	v_readlane_b32 s87, v243, 23
	v_readlane_b32 s88, v243, 24
	v_readlane_b32 s89, v243, 25
	v_readlane_b32 s90, v243, 26
	v_readlane_b32 s91, v243, 27
	v_readlane_b32 s92, v243, 28
	v_readlane_b32 s93, v243, 29
	v_readlane_b32 s94, v243, 30
	v_readlane_b32 s95, v243, 31
	v_readlane_b32 s96, v243, 32
	v_readlane_b32 s97, v243, 33
	v_readlane_b32 s98, v243, 34
	v_readlane_b32 s99, v243, 35
	s_nop 4
	s_barrier
